# mode-6 compaction with one LDS atomic per slot, padded after the loop so all later code keeps its previous byte offsets
# speedup vs baseline: 1.0094x; 1.0094x over previous
;     ...
;     for (int it = 0; it < nit; ++it) {
;         const int kt = kt0 + 4 * (it >> 1), kb = it & 1;
;         const int itn = it + 1 < nit ? it + 1 : it;
;         const bf16_t* np = ikp + (size_t)(256 * (itn >> 1) + 32 * (itn & 1)) * NZ; const bf16x8 n0 = *(const bf16x8*)np, n1 = *(const bf16x8*)(np + 16);
;     ...
;         a0 = n0; a1 = n1;
;     }
.Lm6_nb15:
	s_mov_b64 exec, -1
	s_waitcnt vmcnt(0)
	v_mov_b64_e32 v[132:133], v[64:65]
	v_mov_b64_e32 v[134:135], v[66:67]
	v_mov_b64_e32 v[128:129], v[68:69]
	v_mov_b64_e32 v[130:131], v[70:71]
	s_cmp_lg_u32 s25, s1
	s_mov_b32 s18, s1
	s_cbranch_scc1 .Lm6_loop
	s_nop 0
	s_nop 0
	s_nop 0
	s_nop 0
	s_nop 0
	s_nop 0
	s_nop 0
	s_nop 0
	s_nop 0
	s_nop 0
	s_nop 0
	s_nop 0
	s_nop 0
	s_nop 0
	s_nop 0
	s_nop 0
